# s_setprio flips removed from the four 256x256 GEMM k-loops (on top of the attention loop rewrite)
# speedup vs baseline: 1.0404x; 1.0020x over previous
; #define MFMA32(a, b, c) __builtin_amdgcn_mfma_f32_32x32x16_bf16((a), (b), (c), 0, 0, 0)
; template <int EPI, bool RSQ>
; DI void gemm_phase8(const Params& p, int l, const u16* __restrict__ A, int lda, const u16* __restrict__ Bt, int K,
;                    int ntiles_n, int gofs, char* smem, bool latonly = false) {
;     ...
;     {
;       const char* As = smem + cur * 73728;
;       const char* Bs = As + 36864;
;       const char* ap = As + (wr * 128 + lr) * 144 + lh * 16;
;       const char* bp = Bs + (wc * 64 + lr) * 144 + lh * 16;
;       bf16x8 fa[3][2], fb[2][2];
;       fa[0][0] = *(const bf16x8*)(ap);
;       fa[0][1] = *(const bf16x8*)(ap + 32 * 144);
;       fb[0][0] = *(const bf16x8*)(bp);
;       fb[0][1] = *(const bf16x8*)(bp + 32 * 144);
;       fa[1][0] = *(const bf16x8*)(ap + 2 * 32 * 144);
;       fa[1][1] = *(const bf16x8*)(ap + 3 * 32 * 144);
;       fb[1][0] = *(const bf16x8*)(bp + 32);
;       fb[1][1] = *(const bf16x8*)(bp + 32 * 144 + 32);
; #pragma unroll
;       for (int u = 0; u < 8; ++u) {
;         const int ks = u >> 1, hf = u & 1, ca = u % 3, cb = ks & 1;
;         if (u + 2 < 8) {
;           const int ks2 = (u + 2) >> 1, hf2 = (u + 2) & 1, cn = (u + 2) % 3;
;           fa[cn][0] = *(const bf16x8*)(ap + (2 * hf2) * 32 * 144 + ks2 * 32);
;           fa[cn][1] = *(const bf16x8*)(ap + (2 * hf2 + 1) * 32 * 144 + ks2 * 32);
;         }
;         __builtin_amdgcn_sched_barrier(0);
;         __builtin_amdgcn_s_setprio(1);
;         acc[2 * hf][0] = MFMA32(fa[ca][0], fb[cb][0], acc[2 * hf][0]);
;         acc[2 * hf][1] = MFMA32(fa[ca][0], fb[cb][1], acc[2 * hf][1]);
;         acc[2 * hf + 1][0] = MFMA32(fa[ca][1], fb[cb][0], acc[2 * hf + 1][0]);
;         acc[2 * hf + 1][1] = MFMA32(fa[ca][1], fb[cb][1], acc[2 * hf + 1][1]);
;         __builtin_amdgcn_s_setprio(0);
;         __builtin_amdgcn_sched_barrier(0);
;         if (u == 0) {
;           if (Lset_valid) issue(La, Lb);
;           __builtin_amdgcn_sched_barrier(0);
;         }
;         if (hf == 1 && ks + 2 < 4) {
;           fb[cb][0] = *(const bf16x8*)(bp + (ks + 2) * 32);
;           fb[cb][1] = *(const bf16x8*)(bp + 32 * 144 + (ks + 2) * 32);
;           __builtin_amdgcn_sched_barrier(0);
;         }
;       }
.LBB1_215:
	s_mul_i32 s2, s9, 0x12000
	s_add_i32 s2, s2, 0
	v_add_u32_e32 v160, s2, v202
	v_add_u32_e32 v218, v160, v203
	v_add_u32_e32 v160, s2, v213
	v_add_u32_e32 v219, v160, v203
	ds_read_b128 v[176:179], v219 offset:36864
	ds_read_b128 v[160:163], v219 offset:36896
	ds_read_b128 v[188:191], v218 offset:9216
	ds_read_b128 v[180:183], v218 offset:13824
	ds_read_b128 v[184:187], v219 offset:41472
	ds_read_b128 v[164:167], v219 offset:41504
	ds_read_b128 v[220:223], v218
	ds_read_b128 v[172:175], v218 offset:32
	ds_read_b128 v[224:227], v218 offset:4608
	ds_read_b128 v[168:171], v218 offset:4640
	v_subrev_u32_e32 v238, s2, v201
	v_add_u32_e32 v238, 0x12000, v238
	s_waitcnt lgkmcnt(3)
	v_mfma_f32_32x32x16_bf16 v[112:127], v[220:223], v[176:179], v[112:127]
	v_mfma_f32_32x32x16_bf16 v[48:63], v[220:223], v[184:187], v[48:63]
	s_waitcnt lgkmcnt(1)
	v_mfma_f32_32x32x16_bf16 v[96:111], v[224:227], v[176:179], v[96:111]
	v_mfma_f32_32x32x16_bf16 v[32:47], v[224:227], v[184:187], v[32:47]
.LBB1_220:
	ds_read_b128 v[220:223], v218 offset:9248
	ds_read_b128 v[224:227], v218 offset:13856
	v_mfma_f32_32x32x16_bf16 v[80:95], v[188:191], v[176:179], v[80:95]
	v_mfma_f32_32x32x16_bf16 v[16:31], v[188:191], v[184:187], v[16:31]
	v_mfma_f32_32x32x16_bf16 v[64:79], v[180:183], v[176:179], v[64:79]
	v_mfma_f32_32x32x16_bf16 v[0:15], v[180:183], v[184:187], v[0:15]
	ds_read_b128 v[176:179], v219 offset:36928
	ds_read_b128 v[180:183], v219 offset:41536
	ds_read_b128 v[184:187], v218 offset:64
	ds_read_b128 v[188:191], v218 offset:4672
	v_mfma_f32_32x32x16_bf16 v[112:127], v[172:175], v[160:163], v[112:127]
	v_mfma_f32_32x32x16_bf16 v[48:63], v[172:175], v[164:167], v[48:63]
	s_waitcnt lgkmcnt(6)
	v_mfma_f32_32x32x16_bf16 v[96:111], v[168:171], v[160:163], v[96:111]
	v_mfma_f32_32x32x16_bf16 v[32:47], v[168:171], v[164:167], v[32:47]
	ds_read_b128 v[168:171], v218 offset:9280
	ds_read_b128 v[172:175], v218 offset:13888
	s_waitcnt lgkmcnt(7)
	v_mfma_f32_32x32x16_bf16 v[80:95], v[220:223], v[160:163], v[80:95]
	v_mfma_f32_32x32x16_bf16 v[16:31], v[220:223], v[164:167], v[16:31]
	s_waitcnt lgkmcnt(6)
	v_mfma_f32_32x32x16_bf16 v[64:79], v[224:227], v[160:163], v[64:79]
	v_mfma_f32_32x32x16_bf16 v[0:15], v[224:227], v[164:167], v[0:15]
	ds_read_b128 v[160:163], v219 offset:36960
	ds_read_b128 v[164:167], v219 offset:41568
	ds_read_b128 v[220:223], v218 offset:96
	ds_read_b128 v[224:227], v218 offset:4704
	s_waitcnt lgkmcnt(7)
	v_mfma_f32_32x32x16_bf16 v[112:127], v[184:187], v[176:179], v[112:127]
	v_mfma_f32_32x32x16_bf16 v[48:63], v[184:187], v[180:183], v[48:63]
	s_waitcnt lgkmcnt(6)
	v_mfma_f32_32x32x16_bf16 v[96:111], v[188:191], v[176:179], v[96:111]
	v_mfma_f32_32x32x16_bf16 v[32:47], v[188:191], v[180:183], v[32:47]
	ds_read_b128 v[184:187], v218 offset:9312
	ds_read_b128 v[188:191], v218 offset:13920
	s_waitcnt vmcnt(6)
	ds_write_b128 v238, v[128:131]
	ds_write_b128 v238, v[132:135] offset:36864
	s_waitcnt lgkmcnt(9)
	v_mfma_f32_32x32x16_bf16 v[80:95], v[168:171], v[176:179], v[80:95]
	v_mfma_f32_32x32x16_bf16 v[16:31], v[168:171], v[180:183], v[16:31]
	s_waitcnt lgkmcnt(8)
	v_mfma_f32_32x32x16_bf16 v[64:79], v[172:175], v[176:179], v[64:79]
	v_mfma_f32_32x32x16_bf16 v[0:15], v[172:175], v[180:183], v[0:15]
	s_waitcnt vmcnt(3)
	ds_write_b128 v238, v[136:139] offset:9216
	ds_write_b128 v238, v[140:143] offset:46080
	ds_write_b128 v238, v[144:147] offset:18432
	s_waitcnt lgkmcnt(8)
	v_mfma_f32_32x32x16_bf16 v[112:127], v[220:223], v[160:163], v[112:127]
	v_mfma_f32_32x32x16_bf16 v[48:63], v[220:223], v[164:167], v[48:63]
	s_waitcnt lgkmcnt(7)
	v_mfma_f32_32x32x16_bf16 v[96:111], v[224:227], v[160:163], v[96:111]
	v_mfma_f32_32x32x16_bf16 v[32:47], v[224:227], v[164:167], v[32:47]
	s_waitcnt vmcnt(0)
	ds_write_b128 v238, v[148:151] offset:55296
	ds_write_b128 v238, v[152:155] offset:27648
	ds_write_b128 v238, v[156:159] offset:64512
	s_waitcnt lgkmcnt(9)
	v_mfma_f32_32x32x16_bf16 v[80:95], v[184:187], v[160:163], v[80:95]
	v_mfma_f32_32x32x16_bf16 v[16:31], v[184:187], v[164:167], v[16:31]
	s_waitcnt lgkmcnt(8)
	v_mfma_f32_32x32x16_bf16 v[64:79], v[188:191], v[160:163], v[64:79]
	v_mfma_f32_32x32x16_bf16 v[0:15], v[188:191], v[164:167], v[0:15]
	v_cndmask_b32_e64 v220, 0, 1, s[0:1]
	v_cmp_ne_u32_e64 s[40:41], 1, v220
	s_andn2_b64 vcc, exec, s[0:1]
	s_mov_b64 s[0:1], 0
	s_cbranch_vccnz .Lgemm_issue_done_1
	s_lshl_b32 s0, s12, 7
	s_waitcnt vmcnt(1)
	v_add_u32_e32 v152, s0, v215
	s_waitcnt vmcnt(0)
	v_add_u32_e32 v156, s0, v216
	v_readlane_b32 s0, v235, 59
	v_readlane_b32 s1, v235, 60
	global_load_dwordx4 v[128:131], v152, s[62:63]
	v_add_u32_e32 v136, 0x20000, v152
	v_add_u32_e32 v140, 0x20000, v156
	v_add_u32_e32 v144, 0x40000, v152
	v_add_u32_e32 v148, 0x40000, v156
	global_load_dwordx4 v[132:135], v156, s[0:1]
	v_add_u32_e32 v152, 0x60000, v152
	v_add_u32_e32 v156, 0x60000, v156
	global_load_dwordx4 v[136:139], v136, s[62:63]
	s_add_i32 s12, s12, 1
	global_load_dwordx4 v[140:143], v140, s[0:1]
	s_cmp_lg_u32 s12, 16
	global_load_dwordx4 v[144:147], v144, s[62:63]
	s_nop 0
	global_load_dwordx4 v[148:151], v148, s[0:1]
	s_nop 0
	global_load_dwordx4 v[152:155], v152, s[62:63]
	s_nop 0
	global_load_dwordx4 v[156:159], v156, s[0:1]
	s_mov_b64 s[0:1], -1
	s_cbranch_scc1 .Lgemm_issue_done_1
	v_readlane_b32 s0, v236, 44
	s_add_i32 s10, s10, s0
	s_cmpk_gt_i32 s10, 0x175
	s_mov_b64 s[0:1], 0
	s_cbranch_scc1 .LBB1_219
	s_mul_hi_i32 s0, s10, 0x2e8ba2e9
	s_lshr_b32 s1, s0, 31
	s_ashr_i32 s0, s0, 4
	s_add_i32 s0, s0, s1
	s_lshl_b32 s1, s0, 3
	s_sub_i32 s2, 34, s1
	s_min_u32 s2, s2, 8
	v_cvt_f32_ubyte0_e32 v215, s2
	v_rcp_iflag_f32_e32 v215, v215
	s_sub_i32 s5, 0, s2
	s_mulk_i32 s0, 0xffa8
	s_add_i32 s0, s0, s10
	v_mul_f32_e32 v215, 0x4f7ffffe, v215
	v_cvt_u32_f32_e32 v215, v215
	s_abs_i32 s4, s0
	s_ashr_i32 s3, s0, 31
	v_readfirstlane_b32 s6, v215
	s_mul_i32 s5, s5, s6
	s_mul_hi_u32 s5, s6, s5
	s_add_i32 s6, s6, s5
	s_mul_hi_u32 s5, s4, s6
	s_mul_i32 s6, s5, s2
	s_sub_i32 s4, s4, s6
	s_add_i32 s6, s5, 1
	s_sub_i32 s7, s4, s2
	s_cmp_ge_u32 s4, s2
	s_cselect_b32 s5, s6, s5
	s_cselect_b32 s4, s7, s4
	s_add_i32 s6, s5, 1
	s_cmp_ge_u32 s4, s2
	s_cselect_b32 s4, s6, s5
	s_xor_b32 s4, s4, s3
	s_sub_i32 s3, s4, s3
	v_readlane_b32 s4, v236, 54
	s_add_i32 s1, s1, s4
	s_mul_i32 s2, s3, s2
	s_add_i32 s1, s1, s0
	s_sub_i32 s0, s1, s2
	v_lshl_add_u32 v215, s0, 19, v214
	v_lshl_add_u32 v216, s3, 19, v214
	s_mov_b64 s[0:1], -1

; template <int EPI, bool RSQ>
; DI void gemm_phase8(const Params& p, int l, const u16* __restrict__ A, int lda, const u16* __restrict__ Bt, int K,
;                    int ntiles_n, int gofs, char* smem, bool latonly = false) {
;     ...
;   auto issue = [&](u32x4 (&qa)[4], u32x4 (&qb)[4]) {
; #pragma unroll
;     for (int i = 0; i < 4; ++i) {
;       qa[i] = *(const u32x4*)((const char*)A + (LAo + i * strideA + (unsigned)Lkt * 128u));
;     ...
;     {
;       const char* As = smem + cur * 73728;
;       const char* Bs = As + 36864;
;       const char* ap = As + (wr * 128 + lr) * 144 + lh * 16;
;       const char* bp = Bs + (wc * 64 + lr) * 144 + lh * 16;
;       bf16x8 fa[3][2], fb[2][2];
;       fa[0][0] = *(const bf16x8*)(ap);
;       fa[0][1] = *(const bf16x8*)(ap + 32 * 144);
;       fb[0][0] = *(const bf16x8*)(bp);
;       fb[0][1] = *(const bf16x8*)(bp + 32 * 144);
;       fa[1][0] = *(const bf16x8*)(ap + 2 * 32 * 144);
;       fa[1][1] = *(const bf16x8*)(ap + 3 * 32 * 144);
;       fb[1][0] = *(const bf16x8*)(bp + 32);
;       fb[1][1] = *(const bf16x8*)(bp + 32 * 144 + 32);
; #pragma unroll
;       for (int u = 0; u < 8; ++u) {
;         const int ks = u >> 1, hf = u & 1, ca = u % 3, cb = ks & 1;
;         if (u + 2 < 8) {
;           const int ks2 = (u + 2) >> 1, hf2 = (u + 2) & 1, cn = (u + 2) % 3;
;           fa[cn][0] = *(const bf16x8*)(ap + (2 * hf2) * 32 * 144 + ks2 * 32);
;           fa[cn][1] = *(const bf16x8*)(ap + (2 * hf2 + 1) * 32 * 144 + ks2 * 32);
;         }
;         __builtin_amdgcn_sched_barrier(0);
;         __builtin_amdgcn_s_setprio(1);
;         acc[2 * hf][0] = MFMA32(fa[ca][0], fb[cb][0], acc[2 * hf][0]);
;         acc[2 * hf][1] = MFMA32(fa[ca][0], fb[cb][1], acc[2 * hf][1]);
;         acc[2 * hf + 1][0] = MFMA32(fa[ca][1], fb[cb][0], acc[2 * hf + 1][0]);
;         acc[2 * hf + 1][1] = MFMA32(fa[ca][1], fb[cb][1], acc[2 * hf + 1][1]);
;         __builtin_amdgcn_s_setprio(0);
;         __builtin_amdgcn_sched_barrier(0);
;         if (u == 0) {
;           if (Lset_valid) issue(La, Lb);
;           __builtin_amdgcn_sched_barrier(0);
;         }
;         if (hf == 1 && ks + 2 < 4) {
;           fb[cb][0] = *(const bf16x8*)(bp + (ks + 2) * 32);
;           fb[cb][1] = *(const bf16x8*)(bp + 32 * 144 + (ks + 2) * 32);
;           __builtin_amdgcn_sched_barrier(0);
;         }
;       }
.LBB1_1301:
	s_mul_i32 s2, s31, 0x12000
	s_add_i32 s2, s2, 0
	v_add_u32_e32 v160, s2, v216
	v_add_u32_e32 v218, v160, v203
	v_add_u32_e32 v160, s2, v213
	v_add_u32_e32 v219, v160, v203
	ds_read_b128 v[176:179], v219 offset:36864
	ds_read_b128 v[160:163], v219 offset:36896
	ds_read_b128 v[188:191], v218 offset:9216
	ds_read_b128 v[180:183], v218 offset:13824
	ds_read_b128 v[184:187], v219 offset:41472
	ds_read_b128 v[164:167], v219 offset:41504
	ds_read_b128 v[220:223], v218
	ds_read_b128 v[172:175], v218 offset:32
	ds_read_b128 v[224:227], v218 offset:4608
	ds_read_b128 v[168:171], v218 offset:4640
	v_subrev_u32_e32 v238, s2, v215
	v_add_u32_e32 v238, 0x12000, v238
	s_waitcnt lgkmcnt(3)
	v_mfma_f32_32x32x16_bf16 v[112:127], v[220:223], v[176:179], v[112:127]
	v_mfma_f32_32x32x16_bf16 v[48:63], v[220:223], v[184:187], v[48:63]
	s_waitcnt lgkmcnt(1)
	v_mfma_f32_32x32x16_bf16 v[96:111], v[224:227], v[176:179], v[96:111]
	v_mfma_f32_32x32x16_bf16 v[32:47], v[224:227], v[184:187], v[32:47]
.LBB1_1308:
	ds_read_b128 v[220:223], v218 offset:9248
	ds_read_b128 v[224:227], v218 offset:13856
	v_mfma_f32_32x32x16_bf16 v[80:95], v[188:191], v[176:179], v[80:95]
	v_mfma_f32_32x32x16_bf16 v[16:31], v[188:191], v[184:187], v[16:31]
	v_mfma_f32_32x32x16_bf16 v[64:79], v[180:183], v[176:179], v[64:79]
	v_mfma_f32_32x32x16_bf16 v[0:15], v[180:183], v[184:187], v[0:15]
	ds_read_b128 v[176:179], v219 offset:36928
	ds_read_b128 v[180:183], v219 offset:41536
	ds_read_b128 v[184:187], v218 offset:64
	ds_read_b128 v[188:191], v218 offset:4672
	v_mfma_f32_32x32x16_bf16 v[112:127], v[172:175], v[160:163], v[112:127]
	v_mfma_f32_32x32x16_bf16 v[48:63], v[172:175], v[164:167], v[48:63]
	s_waitcnt lgkmcnt(6)
	v_mfma_f32_32x32x16_bf16 v[96:111], v[168:171], v[160:163], v[96:111]
	v_mfma_f32_32x32x16_bf16 v[32:47], v[168:171], v[164:167], v[32:47]
	ds_read_b128 v[168:171], v218 offset:9280
	ds_read_b128 v[172:175], v218 offset:13888
	s_waitcnt lgkmcnt(7)
	v_mfma_f32_32x32x16_bf16 v[80:95], v[220:223], v[160:163], v[80:95]
	v_mfma_f32_32x32x16_bf16 v[16:31], v[220:223], v[164:167], v[16:31]
	s_waitcnt lgkmcnt(6)
	v_mfma_f32_32x32x16_bf16 v[64:79], v[224:227], v[160:163], v[64:79]
	v_mfma_f32_32x32x16_bf16 v[0:15], v[224:227], v[164:167], v[0:15]
	ds_read_b128 v[160:163], v219 offset:36960
	ds_read_b128 v[164:167], v219 offset:41568
	ds_read_b128 v[220:223], v218 offset:96
	ds_read_b128 v[224:227], v218 offset:4704
	s_waitcnt lgkmcnt(7)
	v_mfma_f32_32x32x16_bf16 v[112:127], v[184:187], v[176:179], v[112:127]
	v_mfma_f32_32x32x16_bf16 v[48:63], v[184:187], v[180:183], v[48:63]
	s_waitcnt lgkmcnt(6)
	v_mfma_f32_32x32x16_bf16 v[96:111], v[188:191], v[176:179], v[96:111]
	v_mfma_f32_32x32x16_bf16 v[32:47], v[188:191], v[180:183], v[32:47]
	ds_read_b128 v[184:187], v218 offset:9312
	ds_read_b128 v[188:191], v218 offset:13920
	s_waitcnt vmcnt(6)
	ds_write_b128 v238, v[128:131]
	ds_write_b128 v238, v[132:135] offset:36864
	s_waitcnt lgkmcnt(9)
	v_mfma_f32_32x32x16_bf16 v[80:95], v[168:171], v[176:179], v[80:95]
	v_mfma_f32_32x32x16_bf16 v[16:31], v[168:171], v[180:183], v[16:31]
	s_waitcnt lgkmcnt(8)
	v_mfma_f32_32x32x16_bf16 v[64:79], v[172:175], v[176:179], v[64:79]
	v_mfma_f32_32x32x16_bf16 v[0:15], v[172:175], v[180:183], v[0:15]
	s_waitcnt vmcnt(3)
	ds_write_b128 v238, v[136:139] offset:9216
	ds_write_b128 v238, v[140:143] offset:46080
	ds_write_b128 v238, v[144:147] offset:18432
	s_waitcnt lgkmcnt(8)
	v_mfma_f32_32x32x16_bf16 v[112:127], v[220:223], v[160:163], v[112:127]
	v_mfma_f32_32x32x16_bf16 v[48:63], v[220:223], v[164:167], v[48:63]
	s_waitcnt lgkmcnt(7)
	v_mfma_f32_32x32x16_bf16 v[96:111], v[224:227], v[160:163], v[96:111]
	v_mfma_f32_32x32x16_bf16 v[32:47], v[224:227], v[164:167], v[32:47]
	s_waitcnt vmcnt(0)
	ds_write_b128 v238, v[148:151] offset:55296
	ds_write_b128 v238, v[152:155] offset:27648
	ds_write_b128 v238, v[156:159] offset:64512
	s_waitcnt lgkmcnt(9)
	v_mfma_f32_32x32x16_bf16 v[80:95], v[184:187], v[160:163], v[80:95]
	v_mfma_f32_32x32x16_bf16 v[16:31], v[184:187], v[164:167], v[16:31]
	s_waitcnt lgkmcnt(8)
	v_mfma_f32_32x32x16_bf16 v[64:79], v[188:191], v[160:163], v[64:79]
	v_mfma_f32_32x32x16_bf16 v[0:15], v[188:191], v[164:167], v[0:15]
	v_cndmask_b32_e64 v220, 0, 1, s[8:9]
	v_cmp_ne_u32_e64 s[2:3], 1, v220
	s_andn2_b64 vcc, exec, s[8:9]
	s_mov_b64 s[8:9], 0
	s_cbranch_vccnz .Lgemm_issue_done_2
	s_lshl_b32 s8, s37, 7
	s_waitcnt vmcnt(1)
	v_add_u32_e32 v152, s8, v214
	s_waitcnt vmcnt(0)
	v_add_u32_e32 v156, s8, v202
	global_load_dwordx4 v[128:131], v152, s[62:63]
	global_load_dwordx4 v[132:135], v156, s[6:7]
	v_add_u32_e32 v136, 0x20000, v152
	v_add_u32_e32 v140, 0x20000, v156
	v_add_u32_e32 v144, 0x40000, v152
	v_add_u32_e32 v148, 0x40000, v156
	v_add_u32_e32 v152, 0x60000, v152
	v_add_u32_e32 v156, 0x60000, v156
	global_load_dwordx4 v[136:139], v136, s[62:63]
	s_add_i32 s37, s37, 1
	global_load_dwordx4 v[140:143], v140, s[6:7]
	s_cmp_lg_u32 s37, 16
	global_load_dwordx4 v[144:147], v144, s[62:63]
	s_mov_b64 s[8:9], -1
	global_load_dwordx4 v[148:151], v148, s[6:7]
	s_nop 0
	global_load_dwordx4 v[152:155], v152, s[62:63]
	s_nop 0
	global_load_dwordx4 v[156:159], v156, s[6:7]
	s_cbranch_scc1 .Lgemm_issue_done_2
	v_readlane_b32 s8, v236, 44
	s_add_i32 s34, s34, s8
	s_cmp_ge_i32 s34, s21
	s_mov_b64 s[8:9], 0
	s_cbranch_scc1 .LBB1_1307
	s_ashr_i32 s8, s34, 31
	s_lshr_b32 s8, s8, 27
	s_add_i32 s8, s34, s8
	s_ashr_i32 s9, s8, 5
	s_lshl_b32 s9, s9, 3
	s_sub_i32 s10, s20, s9
	s_min_i32 s10, s10, 8
	s_abs_i32 s11, s10
	v_cvt_f32_u32_e32 v202, s11
	s_sub_i32 s14, 0, s11
	s_andn2_b32 s8, s8, 31
	s_sub_i32 s12, s34, s8
	v_rcp_iflag_f32_e32 v202, v202
	s_abs_i32 s8, s12
	s_xor_b32 s13, s12, s10
	s_ashr_i32 s13, s13, 31
	v_mul_f32_e32 v202, 0x4f7ffffe, v202
	v_cvt_u32_f32_e32 v202, v202
	s_nop 0
	v_readfirstlane_b32 s15, v202
	s_mul_i32 s14, s14, s15
	s_mul_hi_u32 s14, s15, s14
	s_add_i32 s15, s15, s14
	s_mul_hi_u32 s14, s8, s15
	s_mul_i32 s15, s14, s11
	s_sub_i32 s8, s8, s15
	s_add_i32 s16, s14, 1
	s_sub_i32 s15, s8, s11
	s_cmp_ge_u32 s8, s11
	s_cselect_b32 s14, s16, s14
	s_cselect_b32 s8, s15, s8
	s_add_i32 s15, s14, 1
	s_cmp_ge_u32 s8, s11
	s_cselect_b32 s8, s15, s14
	s_xor_b32 s8, s8, s13
	s_sub_i32 s8, s8, s13
	s_mul_i32 s10, s8, s10
	s_sub_i32 s10, s12, s10
	s_and_b64 vcc, exec, s[40:41]
	s_add_i32 s9, s10, s9
	s_cbranch_vccnz .LBB1_1306
	s_ashr_i32 s10, s9, 4
	s_mul_i32 s10, s10, 17
	s_and_b32 s9, s9, 15
	s_add_i32 s9, s9, s10
	s_add_i32 s9, s9, 1

; template <int EPI, bool RSQ>
; DI void gemm_phase8(const Params& p, int l, const u16* __restrict__ A, int lda, const u16* __restrict__ Bt, int K,
;                    int ntiles_n, int gofs, char* smem, bool latonly = false) {
;     ...
;   auto issue = [&](u32x4 (&qa)[4], u32x4 (&qb)[4]) {
; #pragma unroll
;     for (int i = 0; i < 4; ++i) {
;       qa[i] = *(const u32x4*)((const char*)A + (LAo + i * strideA + (unsigned)Lkt * 128u));
;     ...
;     {
;       const char* As = smem + cur * 73728;
;       const char* Bs = As + 36864;
;       const char* ap = As + (wr * 128 + lr) * 144 + lh * 16;
;       const char* bp = Bs + (wc * 64 + lr) * 144 + lh * 16;
;       bf16x8 fa[3][2], fb[2][2];
;       fa[0][0] = *(const bf16x8*)(ap);
;       fa[0][1] = *(const bf16x8*)(ap + 32 * 144);
;       fb[0][0] = *(const bf16x8*)(bp);
;       fb[0][1] = *(const bf16x8*)(bp + 32 * 144);
;       fa[1][0] = *(const bf16x8*)(ap + 2 * 32 * 144);
;       fa[1][1] = *(const bf16x8*)(ap + 3 * 32 * 144);
;       fb[1][0] = *(const bf16x8*)(bp + 32);
;       fb[1][1] = *(const bf16x8*)(bp + 32 * 144 + 32);
; #pragma unroll
;       for (int u = 0; u < 8; ++u) {
;         const int ks = u >> 1, hf = u & 1, ca = u % 3, cb = ks & 1;
;         if (u + 2 < 8) {
;           const int ks2 = (u + 2) >> 1, hf2 = (u + 2) & 1, cn = (u + 2) % 3;
;           fa[cn][0] = *(const bf16x8*)(ap + (2 * hf2) * 32 * 144 + ks2 * 32);
;           fa[cn][1] = *(const bf16x8*)(ap + (2 * hf2 + 1) * 32 * 144 + ks2 * 32);
;         }
;         __builtin_amdgcn_sched_barrier(0);
;         __builtin_amdgcn_s_setprio(1);
;         acc[2 * hf][0] = MFMA32(fa[ca][0], fb[cb][0], acc[2 * hf][0]);
;         acc[2 * hf][1] = MFMA32(fa[ca][0], fb[cb][1], acc[2 * hf][1]);
;         acc[2 * hf + 1][0] = MFMA32(fa[ca][1], fb[cb][0], acc[2 * hf + 1][0]);
;         acc[2 * hf + 1][1] = MFMA32(fa[ca][1], fb[cb][1], acc[2 * hf + 1][1]);
;         __builtin_amdgcn_s_setprio(0);
;         __builtin_amdgcn_sched_barrier(0);
;         if (u == 0) {
;           if (Lset_valid) issue(La, Lb);
;           __builtin_amdgcn_sched_barrier(0);
;         }
;         if (hf == 1 && ks + 2 < 4) {
;           fb[cb][0] = *(const bf16x8*)(bp + (ks + 2) * 32);
;           fb[cb][1] = *(const bf16x8*)(bp + 32 * 144 + (ks + 2) * 32);
;           __builtin_amdgcn_sched_barrier(0);
;         }
;       }
.LBB1_1437:
	s_mul_i32 s2, s12, 0x12000
	s_add_i32 s2, s2, 0
	v_add_u32_e32 v160, s2, v215
	v_add_u32_e32 v218, v160, v201
	v_add_u32_e32 v160, s2, v216
	v_add_u32_e32 v219, v160, v201
	ds_read_b128 v[176:179], v219 offset:36864
	ds_read_b128 v[160:163], v219 offset:36896
	ds_read_b128 v[188:191], v218 offset:9216
	ds_read_b128 v[180:183], v218 offset:13824
	ds_read_b128 v[184:187], v219 offset:41472
	ds_read_b128 v[164:167], v219 offset:41504
	ds_read_b128 v[220:223], v218
	ds_read_b128 v[172:175], v218 offset:32
	ds_read_b128 v[224:227], v218 offset:4608
	ds_read_b128 v[168:171], v218 offset:4640
	v_subrev_u32_e32 v238, s2, v214
	v_add_u32_e32 v238, 0x12000, v238
	s_waitcnt lgkmcnt(3)
	v_mfma_f32_32x32x16_bf16 v[112:127], v[220:223], v[176:179], v[112:127]
	v_mfma_f32_32x32x16_bf16 v[96:111], v[220:223], v[184:187], v[96:111]
	s_waitcnt lgkmcnt(1)
	v_mfma_f32_32x32x16_bf16 v[80:95], v[224:227], v[176:179], v[80:95]
	v_mfma_f32_32x32x16_bf16 v[64:79], v[224:227], v[184:187], v[64:79]
.LBB1_1444:
	ds_read_b128 v[220:223], v218 offset:9248
	ds_read_b128 v[224:227], v218 offset:13856
	v_mfma_f32_32x32x16_bf16 v[48:63], v[188:191], v[176:179], v[48:63]
	v_mfma_f32_32x32x16_bf16 v[32:47], v[188:191], v[184:187], v[32:47]
	v_mfma_f32_32x32x16_bf16 v[16:31], v[180:183], v[176:179], v[16:31]
	v_mfma_f32_32x32x16_bf16 v[0:15], v[180:183], v[184:187], v[0:15]
	ds_read_b128 v[176:179], v219 offset:36928
	ds_read_b128 v[180:183], v219 offset:41536
	ds_read_b128 v[184:187], v218 offset:64
	ds_read_b128 v[188:191], v218 offset:4672
	v_mfma_f32_32x32x16_bf16 v[112:127], v[172:175], v[160:163], v[112:127]
	v_mfma_f32_32x32x16_bf16 v[96:111], v[172:175], v[164:167], v[96:111]
	s_waitcnt lgkmcnt(6)
	v_mfma_f32_32x32x16_bf16 v[80:95], v[168:171], v[160:163], v[80:95]
	v_mfma_f32_32x32x16_bf16 v[64:79], v[168:171], v[164:167], v[64:79]
	ds_read_b128 v[168:171], v218 offset:9280
	ds_read_b128 v[172:175], v218 offset:13888
	s_waitcnt lgkmcnt(7)
	v_mfma_f32_32x32x16_bf16 v[48:63], v[220:223], v[160:163], v[48:63]
	v_mfma_f32_32x32x16_bf16 v[32:47], v[220:223], v[164:167], v[32:47]
	s_waitcnt lgkmcnt(6)
	v_mfma_f32_32x32x16_bf16 v[16:31], v[224:227], v[160:163], v[16:31]
	v_mfma_f32_32x32x16_bf16 v[0:15], v[224:227], v[164:167], v[0:15]
	ds_read_b128 v[160:163], v219 offset:36960
	ds_read_b128 v[164:167], v219 offset:41568
	ds_read_b128 v[220:223], v218 offset:96
	ds_read_b128 v[224:227], v218 offset:4704
	s_waitcnt lgkmcnt(7)
	v_mfma_f32_32x32x16_bf16 v[112:127], v[184:187], v[176:179], v[112:127]
	v_mfma_f32_32x32x16_bf16 v[96:111], v[184:187], v[180:183], v[96:111]
	s_waitcnt lgkmcnt(6)
	v_mfma_f32_32x32x16_bf16 v[80:95], v[188:191], v[176:179], v[80:95]
	v_mfma_f32_32x32x16_bf16 v[64:79], v[188:191], v[180:183], v[64:79]
	ds_read_b128 v[184:187], v218 offset:9312
	ds_read_b128 v[188:191], v218 offset:13920
	s_waitcnt vmcnt(6)
	ds_write_b128 v238, v[128:131]
	ds_write_b128 v238, v[132:135] offset:36864
	s_waitcnt lgkmcnt(9)
	v_mfma_f32_32x32x16_bf16 v[48:63], v[168:171], v[176:179], v[48:63]
	v_mfma_f32_32x32x16_bf16 v[32:47], v[168:171], v[180:183], v[32:47]
	s_waitcnt lgkmcnt(8)
	v_mfma_f32_32x32x16_bf16 v[16:31], v[172:175], v[176:179], v[16:31]
	v_mfma_f32_32x32x16_bf16 v[0:15], v[172:175], v[180:183], v[0:15]
	s_waitcnt vmcnt(3)
	ds_write_b128 v238, v[136:139] offset:9216
	ds_write_b128 v238, v[140:143] offset:46080
	ds_write_b128 v238, v[144:147] offset:18432
	s_waitcnt lgkmcnt(8)
	v_mfma_f32_32x32x16_bf16 v[112:127], v[220:223], v[160:163], v[112:127]
	v_mfma_f32_32x32x16_bf16 v[96:111], v[220:223], v[164:167], v[96:111]
	s_waitcnt lgkmcnt(7)
	v_mfma_f32_32x32x16_bf16 v[80:95], v[224:227], v[160:163], v[80:95]
	v_mfma_f32_32x32x16_bf16 v[64:79], v[224:227], v[164:167], v[64:79]
	s_waitcnt vmcnt(0)
	ds_write_b128 v238, v[148:151] offset:55296
	ds_write_b128 v238, v[152:155] offset:27648
	ds_write_b128 v238, v[156:159] offset:64512
	s_waitcnt lgkmcnt(9)
	v_mfma_f32_32x32x16_bf16 v[48:63], v[184:187], v[160:163], v[48:63]
	v_mfma_f32_32x32x16_bf16 v[32:47], v[184:187], v[164:167], v[32:47]
	s_waitcnt lgkmcnt(8)
	v_mfma_f32_32x32x16_bf16 v[16:31], v[188:191], v[160:163], v[16:31]
	v_mfma_f32_32x32x16_bf16 v[0:15], v[188:191], v[164:167], v[0:15]
	v_cndmask_b32_e64 v220, 0, 1, s[6:7]
	v_cmp_ne_u32_e64 s[2:3], 1, v220
	s_andn2_b64 vcc, exec, s[6:7]
	s_mov_b64 s[6:7], 0
	s_cbranch_vccnz .Lgemm_issue_done_3
	s_lshl_b32 s6, s16, 7
	s_waitcnt vmcnt(1)
	v_add_u32_e32 v152, s6, v203
	s_waitcnt vmcnt(0)
	v_add_u32_e32 v156, s6, v213
	global_load_dwordx4 v[128:131], v152, s[62:63]
	global_load_dwordx4 v[132:135], v156, s[0:1]
	v_add_u32_e32 v136, 0x20000, v152
	v_add_u32_e32 v140, 0x20000, v156
	v_add_u32_e32 v144, 0x40000, v152
	v_add_u32_e32 v148, 0x40000, v156
	v_add_u32_e32 v152, 0x60000, v152
	v_add_u32_e32 v156, 0x60000, v156
	global_load_dwordx4 v[136:139], v136, s[62:63]
	s_add_i32 s16, s16, 1
	global_load_dwordx4 v[140:143], v140, s[0:1]
	s_cmp_lg_u32 s16, 16
	global_load_dwordx4 v[144:147], v144, s[62:63]
	s_mov_b64 s[6:7], -1
	global_load_dwordx4 v[148:151], v148, s[0:1]
	s_nop 0
	global_load_dwordx4 v[152:155], v152, s[62:63]
	s_nop 0
	global_load_dwordx4 v[156:159], v156, s[0:1]
	s_cbranch_scc1 .Lgemm_issue_done_3
	v_readlane_b32 s6, v236, 44
	s_add_i32 s13, s13, s6
	s_cmp_ge_i32 s13, s10
	s_mov_b64 s[6:7], 0
	s_cbranch_scc1 .LBB1_1443
	s_mul_hi_i32 s6, s13, 0x2e8ba2e9
	s_lshr_b32 s7, s6, 31
	s_ashr_i32 s6, s6, 5
	s_add_i32 s6, s6, s7
	s_lshl_b32 s7, s6, 3
	s_sub_i32 s8, s20, s7
	s_min_i32 s8, s8, 8
	s_abs_i32 s9, s8
	v_cvt_f32_u32_e32 v203, s9
	s_sub_i32 s19, 0, s9
	s_mulk_i32 s6, 0xff50
	s_add_i32 s16, s6, s13
	v_rcp_iflag_f32_e32 v203, v203
	s_abs_i32 s6, s16
	s_xor_b32 s18, s16, s8
	s_ashr_i32 s18, s18, 31
	v_mul_f32_e32 v203, 0x4f7ffffe, v203
	v_cvt_u32_f32_e32 v203, v203
	s_nop 0
	v_readfirstlane_b32 s22, v203
	s_mul_i32 s19, s19, s22
	s_mul_hi_u32 s19, s22, s19
	s_add_i32 s22, s22, s19
	s_mul_hi_u32 s19, s6, s22
	s_mul_i32 s22, s19, s9
	s_sub_i32 s6, s6, s22
	s_add_i32 s23, s19, 1
	s_sub_i32 s22, s6, s9
	s_cmp_ge_u32 s6, s9
	s_cselect_b32 s19, s23, s19
	s_cselect_b32 s6, s22, s6
	s_add_i32 s22, s19, 1
	s_cmp_ge_u32 s6, s9
	s_cselect_b32 s6, s22, s19
	s_xor_b32 s6, s6, s18
	s_sub_i32 s6, s6, s18
	s_mul_i32 s8, s6, s8
	s_sub_i32 s8, s16, s8
	s_and_b64 vcc, exec, s[40:41]
	s_add_i32 s7, s8, s7
	s_cbranch_vccnz .LBB1_1442
	s_ashr_i32 s8, s7, 4
	s_mul_i32 s8, s8, 17
	s_and_b32 s7, s7, 15
	s_add_i32 s7, s7, s8
	s_add_i32 s7, s7, 1

; template <int EPI, bool RSQ>
; DI void gemm_phase8(const Params& p, int l, const u16* __restrict__ A, int lda, const u16* __restrict__ Bt, int K,
;                    int ntiles_n, int gofs, char* smem, bool latonly = false) {
;     ...
;   auto issue = [&](u32x4 (&qa)[4], u32x4 (&qb)[4]) {
; #pragma unroll
;     for (int i = 0; i < 4; ++i) {
;       qa[i] = *(const u32x4*)((const char*)A + (LAo + i * strideA + (unsigned)Lkt * 128u));
;     ...
;     {
;       const char* As = smem + cur * 73728;
;       const char* Bs = As + 36864;
;       const char* ap = As + (wr * 128 + lr) * 144 + lh * 16;
;       const char* bp = Bs + (wc * 64 + lr) * 144 + lh * 16;
;       bf16x8 fa[3][2], fb[2][2];
;       fa[0][0] = *(const bf16x8*)(ap);
;       fa[0][1] = *(const bf16x8*)(ap + 32 * 144);
;       fb[0][0] = *(const bf16x8*)(bp);
;       fb[0][1] = *(const bf16x8*)(bp + 32 * 144);
;       fa[1][0] = *(const bf16x8*)(ap + 2 * 32 * 144);
;       fa[1][1] = *(const bf16x8*)(ap + 3 * 32 * 144);
;       fb[1][0] = *(const bf16x8*)(bp + 32);
;       fb[1][1] = *(const bf16x8*)(bp + 32 * 144 + 32);
; #pragma unroll
;       for (int u = 0; u < 8; ++u) {
;         const int ks = u >> 1, hf = u & 1, ca = u % 3, cb = ks & 1;
;         if (u + 2 < 8) {
;           const int ks2 = (u + 2) >> 1, hf2 = (u + 2) & 1, cn = (u + 2) % 3;
;           fa[cn][0] = *(const bf16x8*)(ap + (2 * hf2) * 32 * 144 + ks2 * 32);
;           fa[cn][1] = *(const bf16x8*)(ap + (2 * hf2 + 1) * 32 * 144 + ks2 * 32);
;         }
;         __builtin_amdgcn_sched_barrier(0);
;         __builtin_amdgcn_s_setprio(1);
;         acc[2 * hf][0] = MFMA32(fa[ca][0], fb[cb][0], acc[2 * hf][0]);
;         acc[2 * hf][1] = MFMA32(fa[ca][0], fb[cb][1], acc[2 * hf][1]);
;         acc[2 * hf + 1][0] = MFMA32(fa[ca][1], fb[cb][0], acc[2 * hf + 1][0]);
;         acc[2 * hf + 1][1] = MFMA32(fa[ca][1], fb[cb][1], acc[2 * hf + 1][1]);
;         __builtin_amdgcn_s_setprio(0);
;         __builtin_amdgcn_sched_barrier(0);
;         if (u == 0) {
;           if (Lset_valid) issue(La, Lb);
;           __builtin_amdgcn_sched_barrier(0);
;         }
;         if (hf == 1 && ks + 2 < 4) {
;           fb[cb][0] = *(const bf16x8*)(bp + (ks + 2) * 32);
;           fb[cb][1] = *(const bf16x8*)(bp + 32 * 144 + (ks + 2) * 32);
;           __builtin_amdgcn_sched_barrier(0);
;         }
;       }
.LBB1_1512:
	s_mul_i32 s2, s18, 0x12000
	s_add_i32 s2, s2, 0
	v_add_u32_e32 v160, s2, v218
	v_add_u32_e32 v219, v160, v203
	v_add_u32_e32 v160, s2, v213
	v_add_u32_e32 v220, v160, v203
	ds_read_b128 v[176:179], v220 offset:36864
	ds_read_b128 v[160:163], v220 offset:36896
	ds_read_b128 v[188:191], v219 offset:9216
	ds_read_b128 v[180:183], v219 offset:13824
	ds_read_b128 v[184:187], v220 offset:41472
	ds_read_b128 v[164:167], v220 offset:41504
	ds_read_b128 v[222:225], v219
	ds_read_b128 v[172:175], v219 offset:32
	ds_read_b128 v[226:229], v219 offset:4608
	ds_read_b128 v[168:171], v219 offset:4640
	v_subrev_u32_e32 v238, s2, v217
	v_add_u32_e32 v238, 0x12000, v238
	s_waitcnt lgkmcnt(3)
	v_mfma_f32_32x32x16_bf16 v[112:127], v[222:225], v[176:179], v[112:127]
	v_mfma_f32_32x32x16_bf16 v[48:63], v[222:225], v[184:187], v[48:63]
	s_waitcnt lgkmcnt(1)
	v_mfma_f32_32x32x16_bf16 v[96:111], v[226:229], v[176:179], v[96:111]
	v_mfma_f32_32x32x16_bf16 v[32:47], v[226:229], v[184:187], v[32:47]
.LBB1_1519:
	ds_read_b128 v[222:225], v219 offset:9248
	ds_read_b128 v[226:229], v219 offset:13856
	v_mfma_f32_32x32x16_bf16 v[80:95], v[188:191], v[176:179], v[80:95]
	v_mfma_f32_32x32x16_bf16 v[16:31], v[188:191], v[184:187], v[16:31]
	v_mfma_f32_32x32x16_bf16 v[64:79], v[180:183], v[176:179], v[64:79]
	v_mfma_f32_32x32x16_bf16 v[0:15], v[180:183], v[184:187], v[0:15]
	ds_read_b128 v[176:179], v220 offset:36928
	ds_read_b128 v[180:183], v220 offset:41536
	ds_read_b128 v[184:187], v219 offset:64
	ds_read_b128 v[188:191], v219 offset:4672
	v_mfma_f32_32x32x16_bf16 v[112:127], v[172:175], v[160:163], v[112:127]
	v_mfma_f32_32x32x16_bf16 v[48:63], v[172:175], v[164:167], v[48:63]
	s_waitcnt lgkmcnt(6)
	v_mfma_f32_32x32x16_bf16 v[96:111], v[168:171], v[160:163], v[96:111]
	v_mfma_f32_32x32x16_bf16 v[32:47], v[168:171], v[164:167], v[32:47]
	ds_read_b128 v[168:171], v219 offset:9280
	ds_read_b128 v[172:175], v219 offset:13888
	s_waitcnt lgkmcnt(7)
	v_mfma_f32_32x32x16_bf16 v[80:95], v[222:225], v[160:163], v[80:95]
	v_mfma_f32_32x32x16_bf16 v[16:31], v[222:225], v[164:167], v[16:31]
	s_waitcnt lgkmcnt(6)
	v_mfma_f32_32x32x16_bf16 v[64:79], v[226:229], v[160:163], v[64:79]
	v_mfma_f32_32x32x16_bf16 v[0:15], v[226:229], v[164:167], v[0:15]
	ds_read_b128 v[160:163], v220 offset:36960
	ds_read_b128 v[164:167], v220 offset:41568
	ds_read_b128 v[220:223], v219 offset:96
	ds_read_b128 v[224:227], v219 offset:4704
	s_waitcnt lgkmcnt(7)
	v_mfma_f32_32x32x16_bf16 v[112:127], v[184:187], v[176:179], v[112:127]
	v_mfma_f32_32x32x16_bf16 v[48:63], v[184:187], v[180:183], v[48:63]
	s_waitcnt lgkmcnt(6)
	v_mfma_f32_32x32x16_bf16 v[96:111], v[188:191], v[176:179], v[96:111]
	v_mfma_f32_32x32x16_bf16 v[32:47], v[188:191], v[180:183], v[32:47]
	ds_read_b128 v[184:187], v219 offset:9312
	ds_read_b128 v[188:191], v219 offset:13920
	s_waitcnt vmcnt(6)
	ds_write_b128 v238, v[148:151] offset:9216
	ds_write_b128 v238, v[132:135]
	s_waitcnt lgkmcnt(9)
	v_mfma_f32_32x32x16_bf16 v[80:95], v[168:171], v[176:179], v[80:95]
	v_mfma_f32_32x32x16_bf16 v[16:31], v[168:171], v[180:183], v[16:31]
	s_waitcnt lgkmcnt(8)
	v_mfma_f32_32x32x16_bf16 v[64:79], v[172:175], v[176:179], v[64:79]
	v_mfma_f32_32x32x16_bf16 v[0:15], v[172:175], v[180:183], v[0:15]
	s_waitcnt vmcnt(3)
	ds_write_b128 v238, v[136:139] offset:36864
	ds_write_b128 v238, v[144:147] offset:46080
	ds_write_b128 v238, v[152:155] offset:18432
	s_waitcnt lgkmcnt(8)
	v_mfma_f32_32x32x16_bf16 v[112:127], v[220:223], v[160:163], v[112:127]
	v_mfma_f32_32x32x16_bf16 v[48:63], v[220:223], v[164:167], v[48:63]
	s_waitcnt lgkmcnt(7)
	v_mfma_f32_32x32x16_bf16 v[96:111], v[224:227], v[160:163], v[96:111]
	v_mfma_f32_32x32x16_bf16 v[32:47], v[224:227], v[164:167], v[32:47]
	s_waitcnt vmcnt(0)
	ds_write_b128 v238, v[156:159] offset:27648
	ds_write_b128 v238, v[140:143] offset:55296
	ds_write_b128 v238, v[128:131] offset:64512
	s_waitcnt lgkmcnt(9)
	v_mfma_f32_32x32x16_bf16 v[80:95], v[184:187], v[160:163], v[80:95]
	v_mfma_f32_32x32x16_bf16 v[16:31], v[184:187], v[164:167], v[16:31]
	s_waitcnt lgkmcnt(8)
	v_mfma_f32_32x32x16_bf16 v[64:79], v[188:191], v[160:163], v[64:79]
	v_mfma_f32_32x32x16_bf16 v[0:15], v[188:191], v[164:167], v[0:15]
	v_cndmask_b32_e64 v221, 0, 1, s[4:5]
	v_cmp_ne_u32_e64 s[2:3], 1, v221
	s_andn2_b64 vcc, exec, s[4:5]
	s_mov_b64 s[4:5], 0
	s_cbranch_vccnz .Lgemm_issue_done_4
	s_lshl_b32 s4, s31, 7
	s_waitcnt vmcnt(0)
	v_add_u32_e32 v128, s4, v216
	v_add_u32_e32 v129, s4, v214
	v_add_u32_e32 v130, 0x58000, v128
	global_load_dwordx4 v[148:151], v130, s[64:65]
	v_add_u32_e32 v130, 0x58000, v129
	global_load_dwordx4 v[132:135], v128, s[64:65]
	global_load_dwordx4 v[136:139], v129, s[0:1]
	global_load_dwordx4 v[144:147], v130, s[0:1]
	v_add_u32_e32 v130, 0xb0000, v128
	v_add_u32_e32 v128, 0x108000, v128
	global_load_dwordx4 v[152:155], v130, s[64:65]
	v_add_u32_e32 v130, 0xb0000, v129
	global_load_dwordx4 v[156:159], v128, s[64:65]
	v_add_u32_e32 v128, 0x108000, v129
	global_load_dwordx4 v[140:143], v130, s[0:1]
	s_add_i32 s31, s31, 1
	global_load_dwordx4 v[128:131], v128, s[0:1]
	s_cmp_lg_u32 s31, 44
	s_mov_b64 s[4:5], -1
	s_cbranch_scc1 .Lgemm_issue_done_4
	v_readlane_b32 s4, v236, 44
	s_add_i32 s19, s19, s4
	s_cmp_ge_i32 s19, s21
	s_mov_b64 s[4:5], 0
	s_cbranch_scc1 .LBB1_1518
	s_ashr_i32 s4, s19, 31
	s_lshr_b32 s4, s4, 27
	s_add_i32 s4, s19, s4
	s_ashr_i32 s5, s4, 5
	s_lshl_b32 s5, s5, 3
	s_sub_i32 s6, s20, s5
	s_min_i32 s6, s6, 8
	s_abs_i32 s7, s6
	v_cvt_f32_u32_e32 v214, s7
	s_sub_i32 s10, 0, s7
	s_andn2_b32 s4, s4, 31
	s_sub_i32 s8, s19, s4
	v_rcp_iflag_f32_e32 v214, v214
	s_abs_i32 s4, s8
	s_xor_b32 s9, s8, s6
	s_ashr_i32 s9, s9, 31
	v_mul_f32_e32 v214, 0x4f7ffffe, v214
	v_cvt_u32_f32_e32 v214, v214
	s_nop 0
	v_readfirstlane_b32 s11, v214
	s_mul_i32 s10, s10, s11
	s_mul_hi_u32 s10, s11, s10
	s_add_i32 s11, s11, s10
	s_mul_hi_u32 s10, s4, s11
	s_mul_i32 s11, s10, s7
	s_sub_i32 s4, s4, s11
	s_add_i32 s12, s10, 1
	s_sub_i32 s11, s4, s7
	s_cmp_ge_u32 s4, s7
	s_cselect_b32 s10, s12, s10
	s_cselect_b32 s4, s11, s4
	s_add_i32 s11, s10, 1
	s_cmp_ge_u32 s4, s7
	s_cselect_b32 s4, s11, s10
	s_xor_b32 s4, s4, s9
	s_sub_i32 s4, s4, s9
	s_mul_i32 s6, s4, s6
	s_sub_i32 s6, s8, s6
	s_and_b64 vcc, exec, s[40:41]
	s_add_i32 s5, s6, s5
	s_cbranch_vccnz .LBB1_1517
	s_ashr_i32 s6, s5, 4
	s_mul_i32 s6, s6, 17
	s_and_b32 s5, s5, 15
	s_add_i32 s5, s5, s6
	s_add_i32 s5, s5, 1
